# speedup vs baseline: 1.0129x; 1.0053x over previous
; #define LAS __attribute__((address_space(3)))
; __device__ __forceinline__ TileDesc tile_desc(const Params& p, int tile) {
;     TileDesc d; int t = tile; unsigned char* ws = p.ws; d.gw = nullptr;
;     if (t < 2560) { const int j = t / 1280; t -= j * 1280; d.type = 0; d.N = 5120; d.src = p.attn_w_in + (size_t)j * 2048 * 5120; d.dst = (bf16_t*)(ws + OFF_W_AIN + j * SZ_W_AIN); d.gw = p.norm_w + 2 * j * 2048; }
;     else if (t < 3584) { t -= 2560; const int j = t / 512; t -= j * 512; d.type = 2; d.N = 2048; d.src = p.attn_w_out + (size_t)j * 2048 * 2048; d.dst = (bf16_t*)(ws + OFF_W_AOUT + j * SZ_W_OUT); }
;     else if (t < 7680) { t -= 3584; const int j = t / 2048; t -= j * 2048; d.type = 1; d.N = 8192; d.src = p.conv_w_in + (size_t)j * 2048 * 8192; d.dst = (bf16_t*)(ws + OFF_W_CIN + j * SZ_W_CIN); d.gw = p.norm_w + (2 * j + 1) * 2048; }
;     else { t -= 7680; const int j = t / 512; t -= j * 512; d.type = 2; d.N = 2048; d.src = p.conv_w_out + (size_t)j * 2048 * 2048; d.dst = (bf16_t*)(ws + OFF_W_COUT + j * SZ_W_OUT); }
;     d.n0 = (t >> 4) * 64; d.k0 = (t & 15) * 128; return d;
; }
; __device__ __forceinline__ void convert_range(LAS unsigned char* lds, const Params& p, int lo1, int n1, int lo2, int n2, int wi, int nw) {
;     int tid_ = threadIdx.x; asm volatile("" : "+v"(tid_)); const int tid = tid_, g = tid & 15, kp = tid >> 4;
;     int tile = wi; const int hi = n1 + n2;
;     if (tile >= hi) return;
;     f32x4 v[4];
;     TileDesc d = tile_desc(p, tile < n1 ? lo1 + tile : lo2 + tile - n1);
;     { const float* sp = d.src + (size_t)(d.k0 + 2 * kp) * d.N + colmap(d.type, d.n0 + 4 * g);
;       v[0] = *(const f32x4*)sp; v[1] = *(const f32x4*)(sp + d.N); v[2] = *(const f32x4*)(sp + (size_t)64 * d.N); v[3] = *(const f32x4*)(sp + (size_t)65 * d.N); }
;     ...
;         if (more) { d = tile_desc(p, ntile < n1 ? lo1 + ntile : lo2 + ntile - n1);
;             const float* sp = d.src + (size_t)(d.k0 + 2 * kp) * d.N + colmap(d.type, d.n0 + 4 * g);
;             v[0] = *(const f32x4*)sp; v[1] = *(const f32x4*)(sp + d.N); v[2] = *(const f32x4*)(sp + (size_t)64 * d.N); v[3] = *(const f32x4*)(sp + (size_t)65 * d.N); }
.LBB0_13:
	s_mul_i32 s5, s8, 0x2800000
	s_mul_hi_i32 s4, s8, 0x2800000
	s_add_u32 s10, s20, s5
	s_addc_u32 s11, s21, s4
	s_mul_i32 s5, s8, 0x1400000
	s_mul_hi_i32 s4, s8, 0x1400000
	s_add_u32 s6, s28, s5
	s_addc_u32 s7, s29, s4
	s_lshl_b32 s4, s8, 12
	s_ashr_i32 s5, s4, 31
	s_lshl_b64 s[4:5], s[4:5], 2
	s_add_u32 s8, s18, s4
	s_addc_u32 s9, s19, s5
	s_lshl_b32 s4, s2, 7
	v_ashrrev_i32_e32 v3, 3, v18
	s_and_b32 s4, s4, 0x780
	v_and_b32_e32 v27, -2, v3
	v_add_u32_e32 v3, s4, v27
	s_movk_i32 s46, 0x5000
	v_mov_b64_e32 v[4:5], s[10:11]
	v_mad_i64_i32 v[4:5], s[10:11], v3, s46, v[4:5]
	v_ashrrev_i32_e32 v3, 31, v2
	v_lshl_add_u64 v[10:11], v[2:3], 2, v[4:5]
	v_add_co_u32_e32 v12, vcc, s46, v10
	s_mov_b32 s5, 0x140000
	s_nop 0
	v_addc_co_u32_e32 v13, vcc, 0, v11, vcc
	v_add_co_u32_e32 v22, vcc, s5, v10
	s_mov_b32 s5, 0x145000
	s_nop 0
	v_addc_co_u32_e32 v23, vcc, 0, v11, vcc
	v_add_co_u32_e32 v28, vcc, s5, v10
	global_load_dwordx4 v[2:5], v[10:11], off nt
	global_load_dwordx4 v[6:9], v[12:13], off nt
	v_addc_co_u32_e32 v29, vcc, 0, v11, vcc
	global_load_dwordx4 v[10:13], v[22:23], off nt
	global_load_dwordx4 v[14:17], v[28:29], off nt
	v_and_b32_e32 v19, 15, v18
	v_ashrrev_i32_e32 v28, 4, v18
	v_add_u32_e32 v18, 0x200, v18
	s_movk_i32 s10, 0x104
	v_ashrrev_i32_e32 v29, 4, v18
	v_lshl_add_u32 v23, v27, 1, 0
	v_lshl_add_u32 v33, v19, 4, 0
	v_lshlrev_b32_e32 v22, 3, v19
	v_mul_u32_u24_e32 v31, 0x104, v24
	v_mul_lo_u32 v32, v28, s10
	v_mul_lo_u32 v34, v29, s10
	s_waitcnt lgkmcnt(0)
	s_add_i32 s10, s2, s3
	s_mov_b32 s5, 0
	v_mov_b32_e32 v19, 0
	v_or_b32_e32 v30, v20, v21
	s_lshl_b32 s47, s10, 2
	s_lshl_b32 s48, s3, 2
	s_lshl_b32 s49, s10, 7
	s_lshl_b32 s50, s3, 7
	v_add_u32_e32 v31, v23, v31
	v_lshlrev_b32_e32 v18, 1, v22
	v_add_u32_e32 v32, v33, v32
	v_add_u32_e32 v33, v33, v34
	s_mov_b32 s51, s2
	s_branch .LBB0_16
.LBB0_14:
	s_mul_i32 s9, s53, 0x2800000
	s_mul_hi_i32 s8, s53, 0x2800000
	s_add_u32 s54, s20, s9
	s_addc_u32 s55, s21, s8
	s_mul_i32 s9, s53, 0x1400000
	s_mul_hi_i32 s8, s53, 0x1400000
	s_add_u32 s44, s28, s9
	s_addc_u32 s45, s29, s8
	s_lshl_b32 s8, s53, 12
	s_ashr_i32 s9, s8, 31
	s_lshl_b64 s[8:9], s[8:9], 2
	s_add_u32 s8, s18, s8
	s_addc_u32 s9, s19, s9
	s_and_b32 s53, s49, 0x780
	v_add_u32_e32 v3, s53, v27
	v_mov_b64_e32 v[4:5], s[54:55]
	v_mad_i64_i32 v[4:5], s[54:55], v3, s46, v[4:5]
	v_ashrrev_i32_e32 v3, 31, v2
	v_lshl_add_u64 v[10:11], v[2:3], 2, v[4:5]
	v_add_co_u32_e32 v6, vcc, 0x5000, v10
	s_nop 1
	v_addc_co_u32_e32 v7, vcc, 0, v11, vcc
	v_add_co_u32_e32 v12, vcc, 0x140000, v10
	global_load_dwordx4 v[2:5], v[10:11], off nt
	s_nop 0
	global_load_dwordx4 v[6:9], v[6:7], off nt
	v_addc_co_u32_e32 v13, vcc, 0, v11, vcc
	v_add_co_u32_e32 v14, vcc, 0x145000, v10
	s_nop 1
	v_addc_co_u32_e32 v15, vcc, 0, v11, vcc
	global_load_dwordx4 v[10:13], v[12:13], off nt
	s_nop 0
	global_load_dwordx4 v[14:17], v[14:15], off nt

; __device__ __forceinline__ unsigned cvt_pk_bf16(float lo, float hi) { unsigned r; asm volatile("v_cvt_pk_bf16_f32 %0, %1, %2" : "=v"(r) : "v"(lo), "v"(hi)); return r; }
; __device__ __forceinline__ void prologue_phase(LAS unsigned char* lds, const Params& p) {
;     ...
;     for (int r = blockIdx.x * 8 + w; r < MROWS; r += G * 8) {
;         const float* src = r < 8192 ? p.x_prompt + (size_t)r * 2048 : (r < NREAL ? p.x_sample + (size_t)(r - 8192) * 2048 : p.meta + (size_t)((r - NREAL) & 15) * 2048);
;         const bool valid = r < NREAL + NMETA;
;         float ss = 0.f;
; #pragma unroll
;         for (int i = 0; i < 8; ++i) {
;             f32x4 v = *(const f32x4*)(src + 4 * lane + 256 * i);
;             if (!valid) v = (f32x4){0.f, 0.f, 0.f, 0.f};
;             ss += v[0] * v[0] + v[1] * v[1] + v[2] * v[2] + v[3] * v[3];
;             u32x2 o; o.x = cvt_pk_bf16(v[0], v[1]); o.y = cvt_pk_bf16(v[2], v[3]);
;             *(u32x2*)(HB + (size_t)r * 2048 + 4 * lane + 256 * i) = o;
;         }
; #pragma unroll
;         for (int o = 32; o > 0; o >>= 1) ss += __shfl_xor(ss, o);
;         if (lane == 0) { SS[r] = (unsigned long long)(ss * 16777216.f); SS[MROWS + r] = 0ull; SS[2 * MROWS + r] = 0ull; SS[3 * MROWS + r] = 0ull; SS[4 * MROWS + r] = 0ull; }
;     }
.LBB0_44:
	s_or_b64 exec, exec, s[6:7]
	s_waitcnt lgkmcnt(0)
	v_lshl_add_u64 v[10:11], v[10:11], 0, v[8:9]
	global_load_dwordx4 v[20:23], v[10:11], off nt
	v_lshlrev_b64 v[24:25], 12, v[2:3]
	v_lshl_add_u64 v[24:25], v[6:7], 0, v[24:25]
	v_cmp_gt_i32_e32 vcc, s49, v2
	s_waitcnt vmcnt(0)
	s_nop 0
	v_cndmask_b32_e32 v4, 0, v23, vcc
	v_cndmask_b32_e32 v19, 0, v22, vcc
	v_cndmask_b32_e32 v26, 0, v20, vcc
	v_cndmask_b32_e32 v27, 0, v21, vcc
	v_cvt_pk_bf16_f32 v20, v26, v27
	v_cvt_pk_bf16_f32 v21, v19, v4
	global_store_dwordx2 v[24:25], v[20:21], off
	global_load_dwordx4 v[20:23], v[10:11], off offset:1024 nt
	s_waitcnt vmcnt(0)
	v_cndmask_b32_e32 v28, 0, v23, vcc
	v_cndmask_b32_e32 v29, 0, v22, vcc
	v_cndmask_b32_e32 v30, 0, v20, vcc
	v_cndmask_b32_e32 v31, 0, v21, vcc
	v_cvt_pk_bf16_f32 v20, v30, v31
	v_cvt_pk_bf16_f32 v21, v29, v28
	global_store_dwordx2 v[24:25], v[20:21], off offset:512
	global_load_dwordx4 v[20:23], v[10:11], off offset:2048 nt
	s_waitcnt vmcnt(0)
	v_cndmask_b32_e32 v32, 0, v23, vcc
	v_cndmask_b32_e32 v33, 0, v22, vcc
	v_cndmask_b32_e32 v34, 0, v20, vcc
	v_cndmask_b32_e32 v35, 0, v21, vcc
	v_cvt_pk_bf16_f32 v20, v34, v35
	v_cvt_pk_bf16_f32 v21, v33, v32
	global_store_dwordx2 v[24:25], v[20:21], off offset:1024
	global_load_dwordx4 v[20:23], v[10:11], off offset:3072 nt
	v_add_co_u32_e64 v10, s[6:7], s50, v10
	s_waitcnt vmcnt(0)
	v_cndmask_b32_e32 v36, 0, v23, vcc
	v_addc_co_u32_e64 v11, s[6:7], 0, v11, s[6:7]
	v_cndmask_b32_e32 v37, 0, v22, vcc
	v_cndmask_b32_e32 v38, 0, v20, vcc
	v_cndmask_b32_e32 v39, 0, v21, vcc
	v_cvt_pk_bf16_f32 v20, v38, v39
	v_cvt_pk_bf16_f32 v21, v37, v36
	global_store_dwordx2 v[24:25], v[20:21], off offset:1536
	global_load_dwordx4 v[20:23], v[10:11], off nt
	v_cmp_lt_i32_e64 s[6:7], v13, v12
	s_waitcnt vmcnt(0)
	v_cndmask_b32_e32 v40, 0, v23, vcc
	v_cndmask_b32_e32 v41, 0, v22, vcc
	v_cndmask_b32_e32 v42, 0, v20, vcc
	v_cndmask_b32_e32 v43, 0, v21, vcc
	v_cvt_pk_bf16_f32 v20, v42, v43
	v_cvt_pk_bf16_f32 v21, v41, v40
	global_store_dwordx2 v[24:25], v[20:21], off offset:2048
	global_load_dwordx4 v[20:23], v[10:11], off offset:1024 nt
	s_waitcnt vmcnt(0)
	v_cndmask_b32_e32 v44, 0, v23, vcc
	v_cndmask_b32_e32 v45, 0, v22, vcc
	v_cndmask_b32_e32 v46, 0, v20, vcc
	v_cndmask_b32_e32 v47, 0, v21, vcc
	v_cvt_pk_bf16_f32 v20, v46, v47
	v_cvt_pk_bf16_f32 v21, v45, v44
	global_store_dwordx2 v[24:25], v[20:21], off offset:2560
	global_load_dwordx4 v[20:23], v[10:11], off offset:2048 nt
	s_waitcnt vmcnt(0)
	v_cndmask_b32_e32 v48, 0, v23, vcc
	v_cndmask_b32_e32 v49, 0, v22, vcc
	v_cndmask_b32_e32 v50, 0, v20, vcc
	v_cndmask_b32_e32 v51, 0, v21, vcc
	v_cvt_pk_bf16_f32 v20, v50, v51
	v_cvt_pk_bf16_f32 v21, v49, v48
	global_store_dwordx2 v[24:25], v[20:21], off offset:3072
	global_load_dwordx4 v[20:23], v[10:11], off offset:3072 nt
	v_mul_f32_e32 v11, v27, v27
	v_fmac_f32_e32 v11, v26, v26
	v_fmac_f32_e32 v11, v19, v19
	v_fmac_f32_e32 v11, v4, v4
	v_mul_f32_e32 v4, v31, v31
	v_fmac_f32_e32 v4, v30, v30
	v_fmac_f32_e32 v4, v29, v29
	v_fmac_f32_e32 v4, v28, v28
	v_add_f32_e32 v4, v11, v4
	v_mul_f32_e32 v11, v35, v35
	v_fmac_f32_e32 v11, v34, v34
	v_fmac_f32_e32 v11, v33, v33
	v_fmac_f32_e32 v11, v32, v32
	v_add_f32_e32 v4, v4, v11
	v_mul_f32_e32 v11, v39, v39
	v_fmac_f32_e32 v11, v38, v38
	v_fmac_f32_e32 v11, v37, v37
	v_fmac_f32_e32 v11, v36, v36
	v_add_f32_e32 v4, v4, v11
	v_mul_f32_e32 v11, v43, v43
	v_fmac_f32_e32 v11, v42, v42
	v_fmac_f32_e32 v11, v41, v41
	v_fmac_f32_e32 v11, v40, v40
	v_add_f32_e32 v4, v4, v11
	v_mul_f32_e32 v11, v47, v47
	v_fmac_f32_e32 v11, v46, v46
	v_fmac_f32_e32 v11, v45, v45
	v_fmac_f32_e32 v11, v44, v44
	v_add_f32_e32 v4, v4, v11
	v_mul_f32_e32 v11, v51, v51
	v_fmac_f32_e32 v11, v50, v50
	v_fmac_f32_e32 v11, v49, v49
	v_fmac_f32_e32 v11, v48, v48
	v_add_f32_e32 v4, v4, v11
	v_cndmask_b32_e64 v10, v1, v13, s[6:7]
	v_lshlrev_b32_e32 v10, 2, v10
	s_waitcnt vmcnt(0)
	v_cndmask_b32_e32 v21, 0, v21, vcc
	v_cndmask_b32_e32 v19, 0, v22, vcc
	v_cndmask_b32_e32 v20, 0, v20, vcc
	v_mul_f32_e32 v22, v21, v21
	v_fmac_f32_e32 v22, v20, v20
	v_cndmask_b32_e32 v11, 0, v23, vcc
	v_fmac_f32_e32 v22, v19, v19
	v_fmac_f32_e32 v22, v11, v11
	v_add_f32_e32 v4, v4, v22
	ds_bpermute_b32 v10, v10, v4
	v_cmp_lt_i32_e32 vcc, v14, v12
	v_cvt_pk_bf16_f32 v20, v20, v21
	v_cvt_pk_bf16_f32 v21, v19, v11
	global_store_dwordx2 v[24:25], v[20:21], off offset:3584
	s_waitcnt lgkmcnt(0)
	v_add_f32_e32 v4, v4, v10
	v_cndmask_b32_e32 v22, v1, v14, vcc
	v_lshlrev_b32_e32 v22, 2, v22
	ds_bpermute_b32 v10, v22, v4
	v_cmp_lt_i32_e32 vcc, v15, v12
	s_waitcnt lgkmcnt(0)
	v_add_f32_e32 v4, v4, v10
	v_cndmask_b32_e32 v22, v1, v15, vcc
	v_lshlrev_b32_e32 v22, 2, v22
	ds_bpermute_b32 v10, v22, v4
	v_cmp_lt_i32_e32 vcc, v16, v12
	s_waitcnt lgkmcnt(0)
	v_add_f32_e32 v4, v4, v10
	v_cndmask_b32_e32 v22, v1, v16, vcc
	v_lshlrev_b32_e32 v22, 2, v22
	ds_bpermute_b32 v10, v22, v4
	v_cmp_lt_i32_e32 vcc, v17, v12
	s_waitcnt lgkmcnt(0)
	v_add_f32_e32 v4, v4, v10
	v_cndmask_b32_e32 v22, v1, v17, vcc
	v_lshlrev_b32_e32 v22, 2, v22
	ds_bpermute_b32 v10, v22, v4
	v_cmp_lt_i32_e32 vcc, v18, v12
	s_waitcnt lgkmcnt(0)
	v_add_f32_e32 v4, v4, v10
	v_cndmask_b32_e32 v22, v1, v18, vcc
	v_lshlrev_b32_e32 v10, 2, v22
	ds_bpermute_b32 v10, v10, v4
	s_and_saveexec_b64 s[6:7], s[4:5]
	s_cbranch_execz .LBB0_35
	s_waitcnt lgkmcnt(0)
	v_add_f32_e32 v4, v4, v10
	v_mul_f32_e32 v4, 0x4b800000, v4
	v_trunc_f32_e32 v4, v4
	v_mul_f32_e32 v10, 0x2f800000, v4
	v_floor_f32_e32 v10, v10
	v_fmac_f32_e32 v4, 0xcf800000, v10
	v_cvt_u32_f32_e32 v11, v10
	v_cvt_u32_f32_e32 v10, v4
	v_lshl_add_u64 v[20:21], v[2:3], 3, s[80:81]
	s_mov_b32 s11, s10
	v_mov_b64_e32 v[22:23], s[10:11]
	global_store_dwordx2 v[20:21], v[10:11], off
	v_add_co_u32_e32 v10, vcc, 0x30000, v20
	s_nop 1
	v_addc_co_u32_e32 v11, vcc, 0, v21, vcc
	global_store_dwordx2 v[10:11], v[22:23], off offset:2048
	v_add_co_u32_e32 v10, vcc, 0x61000, v20
	s_nop 1
	v_addc_co_u32_e32 v11, vcc, 0, v21, vcc
	global_store_dwordx2 v[10:11], v[22:23], off
	v_add_co_u32_e32 v10, vcc, 0x91000, v20
	s_nop 1
	v_addc_co_u32_e32 v11, vcc, 0, v21, vcc
	global_store_dwordx2 v[10:11], v[22:23], off offset:2048
	v_add_co_u32_e32 v10, vcc, 0xc2000, v20
	s_nop 1
	v_addc_co_u32_e32 v11, vcc, 0, v21, vcc
	global_store_dwordx2 v[10:11], v[22:23], off
	s_branch .LBB0_35
